# wt3_pz + leading half-workgroup at s_setprio 1 from the unit-end barrier through its epilogue, next-unit scheduling and first load segment
# baseline (speedup 1.0000x reference)
.Lmy_sk2:
	s_waitcnt lgkmcnt(0)
	s_setprio 1
	s_barrier
	v_mfma_f32_16x16x32_bf16 v[62:65], v[132:135], v[184:187], v[62:65]
	v_mfma_f32_16x16x32_bf16 v[58:61], v[140:143], v[184:187], v[58:61]
	v_mfma_f32_16x16x32_bf16 v[54:57], v[132:135], v[192:195], v[54:57]
	v_mfma_f32_16x16x32_bf16 v[46:49], v[140:143], v[192:195], v[46:49]
	v_mfma_f32_16x16x32_bf16 v[38:41], v[132:135], v[208:211], v[38:41]
	v_mfma_f32_16x16x32_bf16 v[30:33], v[140:143], v[208:211], v[30:33]
	v_mfma_f32_16x16x32_bf16 v[22:25], v[132:135], v[216:219], v[22:25]
	v_mfma_f32_16x16x32_bf16 v[14:17], v[140:143], v[216:219], v[14:17]
	v_mfma_f32_16x16x32_bf16 v[62:65], v[136:139], v[188:191], v[62:65]
	v_mfma_f32_16x16x32_bf16 v[58:61], v[144:147], v[188:191], v[58:61]
	v_mfma_f32_16x16x32_bf16 v[54:57], v[136:139], v[204:207], v[54:57]
	v_mfma_f32_16x16x32_bf16 v[46:49], v[144:147], v[204:207], v[46:49]
	v_mfma_f32_16x16x32_bf16 v[38:41], v[136:139], v[212:215], v[38:41]
	v_mfma_f32_16x16x32_bf16 v[30:33], v[144:147], v[212:215], v[30:33]
	v_mfma_f32_16x16x32_bf16 v[22:25], v[136:139], v[220:223], v[22:25]
	v_mfma_f32_16x16x32_bf16 v[14:17], v[144:147], v[220:223], v[14:17]
	s_setprio 0
	s_setprio 1
	v_mfma_f32_16x16x32_bf16 v[50:53], v[156:159], v[184:187], v[50:53]
	v_mfma_f32_16x16x32_bf16 v[42:45], v[164:167], v[184:187], v[42:45]
	v_mfma_f32_16x16x32_bf16 v[34:37], v[156:159], v[192:195], v[34:37]
	v_mfma_f32_16x16x32_bf16 v[26:29], v[164:167], v[192:195], v[26:29]
	v_mfma_f32_16x16x32_bf16 v[18:21], v[156:159], v[208:211], v[18:21]
	v_mfma_f32_16x16x32_bf16 v[10:13], v[164:167], v[208:211], v[10:13]
	v_mfma_f32_16x16x32_bf16 v[6:9], v[156:159], v[216:219], v[6:9]
	v_mfma_f32_16x16x32_bf16 v[2:5], v[164:167], v[216:219], v[2:5]
	v_mfma_f32_16x16x32_bf16 v[50:53], v[160:163], v[188:191], v[50:53]
	v_mfma_f32_16x16x32_bf16 v[42:45], v[180:183], v[188:191], v[42:45]
	v_mfma_f32_16x16x32_bf16 v[34:37], v[160:163], v[204:207], v[34:37]
	v_mfma_f32_16x16x32_bf16 v[26:29], v[180:183], v[204:207], v[26:29]
	v_mfma_f32_16x16x32_bf16 v[18:21], v[160:163], v[212:215], v[18:21]
	v_mfma_f32_16x16x32_bf16 v[10:13], v[180:183], v[212:215], v[10:13]
	v_mfma_f32_16x16x32_bf16 v[6:9], v[160:163], v[220:223], v[6:9]
	v_mfma_f32_16x16x32_bf16 v[2:5], v[180:183], v[220:223], v[2:5]
	s_setprio 0
	s_barrier
	s_add_i32 s4, 0, 0x18000
	s_add_i32 s5, 0, 0x1c000
	v_add_u32_e32 v144, s4, v175
	v_add_u32_e32 v170, s5, v175
	ds_read_b128 v[132:135], v144
	ds_read_b128 v[136:139], v144 offset:1024
	ds_read_b128 v[140:143], v144 offset:2048
	ds_read_b128 v[144:147], v144 offset:3072
	ds_read_b128 v[156:159], v170
	ds_read_b128 v[160:163], v170 offset:1024
	ds_read_b128 v[164:167], v170 offset:2048
	ds_read_b128 v[180:183], v170 offset:3072
	s_add_u32 s44, s70, 0x40000
	s_addc_u32 s45, s71, 0
	v_lshl_add_u64 v[202:203], s[44:45], 0, v[98:99]
	s_add_i32 m0, s94, 0x4000
	ds_read_b128 v[184:187], v179 offset:32768
	ds_read_b128 v[188:191], v179 offset:33792
	ds_read_b128 v[192:195], v179 offset:34816
	ds_read_b128 v[204:207], v179 offset:35840
	ds_read_b128 v[208:211], v179 offset:36864
	ds_read_b128 v[212:215], v179 offset:37888
	ds_read_b128 v[216:219], v179 offset:38912
	ds_read_b128 v[220:223], v179 offset:39936
	global_load_lds_dwordx4 v[202:203], off
	v_lshl_add_u64 v[202:203], s[44:45], 0, v[150:151]
	s_add_i32 m0, s94, 0x6000
	s_nop 0
	global_load_lds_dwordx4 v[202:203], off
	s_waitcnt vmcnt(8)
	s_waitcnt lgkmcnt(0)
	s_setprio 1
	s_barrier
	v_mfma_f32_16x16x32_bf16 v[128:131], v[132:135], v[184:187], v[128:131]
	v_mfma_f32_16x16x32_bf16 v[124:127], v[140:143], v[184:187], v[124:127]
	v_mfma_f32_16x16x32_bf16 v[120:123], v[132:135], v[192:195], v[120:123]
	v_mfma_f32_16x16x32_bf16 v[112:115], v[140:143], v[192:195], v[112:115]
	v_mfma_f32_16x16x32_bf16 v[104:107], v[132:135], v[208:211], v[104:107]
	v_mfma_f32_16x16x32_bf16 v[94:97], v[140:143], v[208:211], v[94:97]
	v_mfma_f32_16x16x32_bf16 v[86:89], v[132:135], v[216:219], v[86:89]
	v_mfma_f32_16x16x32_bf16 v[78:81], v[140:143], v[216:219], v[78:81]
	v_mfma_f32_16x16x32_bf16 v[128:131], v[136:139], v[188:191], v[128:131]
	v_mfma_f32_16x16x32_bf16 v[124:127], v[144:147], v[188:191], v[124:127]
	v_mfma_f32_16x16x32_bf16 v[120:123], v[136:139], v[204:207], v[120:123]
	v_mfma_f32_16x16x32_bf16 v[112:115], v[144:147], v[204:207], v[112:115]
	v_mfma_f32_16x16x32_bf16 v[104:107], v[136:139], v[212:215], v[104:107]
	v_mfma_f32_16x16x32_bf16 v[94:97], v[144:147], v[212:215], v[94:97]
	v_mfma_f32_16x16x32_bf16 v[86:89], v[136:139], v[220:223], v[86:89]
	v_mfma_f32_16x16x32_bf16 v[78:81], v[144:147], v[220:223], v[78:81]
	s_setprio 0
	s_setprio 1
	v_mfma_f32_16x16x32_bf16 v[116:119], v[156:159], v[184:187], v[116:119]
	v_mfma_f32_16x16x32_bf16 v[108:111], v[164:167], v[184:187], v[108:111]
	v_mfma_f32_16x16x32_bf16 v[100:103], v[156:159], v[192:195], v[100:103]
	v_mfma_f32_16x16x32_bf16 v[90:93], v[164:167], v[192:195], v[90:93]
	v_mfma_f32_16x16x32_bf16 v[82:85], v[156:159], v[208:211], v[82:85]
	v_mfma_f32_16x16x32_bf16 v[74:77], v[164:167], v[208:211], v[74:77]
	v_mfma_f32_16x16x32_bf16 v[70:73], v[156:159], v[216:219], v[70:73]
	v_mfma_f32_16x16x32_bf16 v[66:69], v[164:167], v[216:219], v[66:69]
	v_mfma_f32_16x16x32_bf16 v[116:119], v[160:163], v[188:191], v[116:119]
	v_mfma_f32_16x16x32_bf16 v[108:111], v[180:183], v[188:191], v[108:111]
	v_mfma_f32_16x16x32_bf16 v[100:103], v[160:163], v[204:207], v[100:103]
	v_mfma_f32_16x16x32_bf16 v[90:93], v[180:183], v[204:207], v[90:93]
	v_mfma_f32_16x16x32_bf16 v[82:85], v[160:163], v[212:215], v[82:85]
	v_mfma_f32_16x16x32_bf16 v[74:77], v[180:183], v[212:215], v[74:77]
	v_mfma_f32_16x16x32_bf16 v[70:73], v[160:163], v[220:223], v[70:73]
	v_mfma_f32_16x16x32_bf16 v[66:69], v[180:183], v[220:223], v[66:69]
	s_setprio 0
	s_barrier
	s_add_i32 s4, s4, s77
	v_lshl_add_u64 v[168:169], v[168:169], 0, s[42:43]
	s_mov_b32 m0, s4
	ds_read_b128 v[184:187], v179 offset:49152
	ds_read_b128 v[188:191], v179 offset:50176
	ds_read_b128 v[192:195], v179 offset:51200
	ds_read_b128 v[204:207], v179 offset:52224
	ds_read_b128 v[208:211], v179 offset:53248
	ds_read_b128 v[212:215], v179 offset:54272
	ds_read_b128 v[216:219], v179 offset:55296
	ds_read_b128 v[220:223], v179 offset:56320
	global_load_lds_dwordx4 v[168:169], off
	s_add_i32 m0, s4, 0x2000
	s_add_u32 s44, s68, 0x40080
	v_lshl_add_u64 v[168:169], v[172:173], 0, s[42:43]
	s_addc_u32 s45, s69, 0
	s_add_i32 s4, s5, s77
	global_load_lds_dwordx4 v[168:169], off
	v_lshl_add_u64 v[168:169], s[44:45], 0, v[148:149]
	s_mov_b32 m0, s4
	s_nop 0
	global_load_lds_dwordx4 v[168:169], off
	v_lshl_add_u64 v[168:169], s[44:45], 0, v[152:153]
	s_add_i32 m0, s4, 0x2000
	s_nop 0
	global_load_lds_dwordx4 v[168:169], off
	v_lshl_add_u64 v[168:169], v[176:177], 0, s[42:43]
	s_add_i32 m0, s94, 0x8000
	s_nop 0
	global_load_lds_dwordx4 v[168:169], off
	v_lshl_add_u64 v[168:169], v[200:201], 0, s[42:43]
	s_add_i32 m0, s94, 0xa000
	s_nop 0
	global_load_lds_dwordx4 v[168:169], off
	s_waitcnt vmcnt(8)
	s_waitcnt lgkmcnt(0)
	s_setprio 1
	s_barrier
	v_mfma_f32_16x16x32_bf16 v[62:65], v[132:135], v[184:187], v[62:65]
	v_mfma_f32_16x16x32_bf16 v[58:61], v[140:143], v[184:187], v[58:61]
	v_mfma_f32_16x16x32_bf16 v[54:57], v[132:135], v[192:195], v[54:57]
	v_mfma_f32_16x16x32_bf16 v[46:49], v[140:143], v[192:195], v[46:49]
	v_mfma_f32_16x16x32_bf16 v[38:41], v[132:135], v[208:211], v[38:41]
	v_mfma_f32_16x16x32_bf16 v[30:33], v[140:143], v[208:211], v[30:33]
	v_mfma_f32_16x16x32_bf16 v[22:25], v[132:135], v[216:219], v[22:25]
	v_mfma_f32_16x16x32_bf16 v[14:17], v[140:143], v[216:219], v[14:17]
	v_mfma_f32_16x16x32_bf16 v[62:65], v[136:139], v[188:191], v[62:65]
	v_mfma_f32_16x16x32_bf16 v[58:61], v[144:147], v[188:191], v[58:61]
	v_mfma_f32_16x16x32_bf16 v[54:57], v[136:139], v[204:207], v[54:57]
	v_mfma_f32_16x16x32_bf16 v[46:49], v[144:147], v[204:207], v[46:49]
	v_mfma_f32_16x16x32_bf16 v[38:41], v[136:139], v[212:215], v[38:41]
	v_mfma_f32_16x16x32_bf16 v[30:33], v[144:147], v[212:215], v[30:33]
	v_mfma_f32_16x16x32_bf16 v[22:25], v[136:139], v[220:223], v[22:25]
	v_mfma_f32_16x16x32_bf16 v[14:17], v[144:147], v[220:223], v[14:17]
	s_setprio 0
	s_setprio 1
	v_mfma_f32_16x16x32_bf16 v[50:53], v[156:159], v[184:187], v[50:53]
	v_mfma_f32_16x16x32_bf16 v[42:45], v[164:167], v[184:187], v[42:45]
	v_mfma_f32_16x16x32_bf16 v[34:37], v[156:159], v[192:195], v[34:37]
	v_mfma_f32_16x16x32_bf16 v[26:29], v[164:167], v[192:195], v[26:29]
	v_mfma_f32_16x16x32_bf16 v[18:21], v[156:159], v[208:211], v[18:21]
	v_mfma_f32_16x16x32_bf16 v[10:13], v[164:167], v[208:211], v[10:13]
	v_mfma_f32_16x16x32_bf16 v[6:9], v[156:159], v[216:219], v[6:9]
	v_mfma_f32_16x16x32_bf16 v[2:5], v[164:167], v[216:219], v[2:5]
	v_mfma_f32_16x16x32_bf16 v[50:53], v[160:163], v[188:191], v[50:53]
	v_mfma_f32_16x16x32_bf16 v[42:45], v[180:183], v[188:191], v[42:45]
	v_mfma_f32_16x16x32_bf16 v[34:37], v[160:163], v[204:207], v[34:37]
	v_mfma_f32_16x16x32_bf16 v[26:29], v[180:183], v[204:207], v[26:29]
	v_mfma_f32_16x16x32_bf16 v[18:21], v[160:163], v[212:215], v[18:21]
	v_mfma_f32_16x16x32_bf16 v[10:13], v[180:183], v[212:215], v[10:13]
	v_mfma_f32_16x16x32_bf16 v[6:9], v[160:163], v[220:223], v[6:9]
	v_mfma_f32_16x16x32_bf16 v[2:5], v[180:183], v[220:223], v[2:5]
	s_setprio 0
	s_barrier
	s_mov_b32 s100, 0
	s_add_i32 s93, s93, 2
	s_add_u32 s0, s0, 0x100
	s_addc_u32 s1, s1, 0
	s_add_u32 s91, s91, 0x100
	s_addc_u32 s92, s92, 0
	s_cmp_gt_u32 s93, 13
	s_cbranch_scc0 .LBB0_322
	s_mov_b32 s100, 1
	s_and_b64 vcc, exec, s[14:15]
	s_cbranch_vccz .LBB0_325
	s_barrier
	s_setprio 1

.LBB0_328:
	s_setprio 0
	s_waitcnt vmcnt(0)
	v_readlane_b32 s8, v255, 31
	v_readlane_b32 s74, v255, 33
	v_readlane_b32 s70, v255, 37
	v_readlane_b32 s9, v255, 32
	v_readlane_b32 s75, v255, 34
	v_readlane_b32 s77, v255, 36
	v_readlane_b32 s71, v255, 38
	s_mov_b64 s[78:79], 0x10000
	s_barrier

.Lmy_sk4:
	s_waitcnt lgkmcnt(0)
	s_setprio 1
	s_barrier
	v_mfma_f32_16x16x32_bf16 v[62:65], v[90:93], v[164:167], v[62:65]
	v_mfma_f32_16x16x32_bf16 v[58:61], v[100:103], v[164:167], v[58:61]
	v_mfma_f32_16x16x32_bf16 v[46:49], v[90:93], v[172:175], v[46:49]
	v_mfma_f32_16x16x32_bf16 v[42:45], v[100:103], v[172:175], v[42:45]
	v_mfma_f32_16x16x32_bf16 v[30:33], v[90:93], v[180:183], v[30:33]
	v_mfma_f32_16x16x32_bf16 v[26:29], v[100:103], v[180:183], v[26:29]
	v_mfma_f32_16x16x32_bf16 v[14:17], v[90:93], v[188:191], v[14:17]
	v_mfma_f32_16x16x32_bf16 v[10:13], v[100:103], v[188:191], v[10:13]
	v_mfma_f32_16x16x32_bf16 v[62:65], v[94:97], v[168:171], v[62:65]
	v_mfma_f32_16x16x32_bf16 v[58:61], v[104:107], v[168:171], v[58:61]
	v_mfma_f32_16x16x32_bf16 v[46:49], v[94:97], v[176:179], v[46:49]
	v_mfma_f32_16x16x32_bf16 v[42:45], v[104:107], v[176:179], v[42:45]
	v_mfma_f32_16x16x32_bf16 v[30:33], v[94:97], v[184:187], v[30:33]
	v_mfma_f32_16x16x32_bf16 v[26:29], v[104:107], v[184:187], v[26:29]
	v_mfma_f32_16x16x32_bf16 v[14:17], v[94:97], v[192:195], v[14:17]
	v_mfma_f32_16x16x32_bf16 v[10:13], v[104:107], v[192:195], v[10:13]
	s_setprio 0
	s_setprio 1
	v_mfma_f32_16x16x32_bf16 v[54:57], v[108:111], v[164:167], v[54:57]
	v_mfma_f32_16x16x32_bf16 v[50:53], v[120:123], v[164:167], v[50:53]
	v_mfma_f32_16x16x32_bf16 v[38:41], v[108:111], v[172:175], v[38:41]
	v_mfma_f32_16x16x32_bf16 v[34:37], v[120:123], v[172:175], v[34:37]
	v_mfma_f32_16x16x32_bf16 v[22:25], v[108:111], v[180:183], v[22:25]
	v_mfma_f32_16x16x32_bf16 v[18:21], v[120:123], v[180:183], v[18:21]
	v_mfma_f32_16x16x32_bf16 v[6:9], v[108:111], v[188:191], v[6:9]
	v_mfma_f32_16x16x32_bf16 v[2:5], v[120:123], v[188:191], v[2:5]
	v_mfma_f32_16x16x32_bf16 v[54:57], v[112:115], v[168:171], v[54:57]
	v_mfma_f32_16x16x32_bf16 v[50:53], v[128:131], v[168:171], v[50:53]
	v_mfma_f32_16x16x32_bf16 v[38:41], v[112:115], v[176:179], v[38:41]
	v_mfma_f32_16x16x32_bf16 v[34:37], v[128:131], v[176:179], v[34:37]
	v_mfma_f32_16x16x32_bf16 v[22:25], v[112:115], v[184:187], v[22:25]
	v_mfma_f32_16x16x32_bf16 v[18:21], v[128:131], v[184:187], v[18:21]
	v_mfma_f32_16x16x32_bf16 v[6:9], v[112:115], v[192:195], v[6:9]
	v_mfma_f32_16x16x32_bf16 v[2:5], v[128:131], v[192:195], v[2:5]
	s_setprio 0
	s_barrier
	s_add_i32 s6, 0, 0x18000
	s_add_i32 s7, 0, 0x1c000
	v_add_u32_e32 v104, s6, v239
	v_add_u32_e32 v128, s7, v239
	ds_read_b128 v[90:93], v104
	ds_read_b128 v[94:97], v104 offset:1024
	ds_read_b128 v[100:103], v104 offset:2048
	ds_read_b128 v[104:107], v104 offset:3072
	ds_read_b128 v[108:111], v128
	ds_read_b128 v[112:115], v128 offset:1024
	ds_read_b128 v[120:123], v128 offset:2048
	ds_read_b128 v[128:131], v128 offset:3072
	s_add_u32 s4, s74, 0x40000
	s_addc_u32 s5, s75, 0
	v_lshl_add_u64 v[214:215], s[4:5], 0, v[98:99]
	s_add_i32 m0, s44, 0x4000
	ds_read_b128 v[164:167], v241 offset:32768
	ds_read_b128 v[168:171], v241 offset:33792
	ds_read_b128 v[172:175], v241 offset:34816
	ds_read_b128 v[176:179], v241 offset:35840
	ds_read_b128 v[180:183], v241 offset:36864
	ds_read_b128 v[184:187], v241 offset:37888
	ds_read_b128 v[188:191], v241 offset:38912
	ds_read_b128 v[192:195], v241 offset:39936
	global_load_lds_dwordx4 v[214:215], off
	v_lshl_add_u64 v[214:215], s[4:5], 0, v[206:207]
	s_add_i32 m0, s44, 0x6000
	s_nop 0
	global_load_lds_dwordx4 v[214:215], off
	s_waitcnt vmcnt(8)
	s_waitcnt lgkmcnt(0)
	s_setprio 1
	s_barrier
	v_mfma_f32_16x16x32_bf16 v[160:163], v[90:93], v[164:167], v[160:163]
	v_mfma_f32_16x16x32_bf16 v[156:159], v[100:103], v[164:167], v[156:159]
	v_mfma_f32_16x16x32_bf16 v[144:147], v[90:93], v[172:175], v[144:147]
	v_mfma_f32_16x16x32_bf16 v[140:143], v[100:103], v[172:175], v[140:143]
	v_mfma_f32_16x16x32_bf16 v[124:127], v[90:93], v[180:183], v[124:127]
	v_mfma_f32_16x16x32_bf16 v[116:119], v[100:103], v[180:183], v[116:119]
	v_mfma_f32_16x16x32_bf16 v[78:81], v[90:93], v[188:191], v[78:81]
	v_mfma_f32_16x16x32_bf16 v[74:77], v[100:103], v[188:191], v[74:77]
	v_mfma_f32_16x16x32_bf16 v[160:163], v[94:97], v[168:171], v[160:163]
	v_mfma_f32_16x16x32_bf16 v[156:159], v[104:107], v[168:171], v[156:159]
	v_mfma_f32_16x16x32_bf16 v[144:147], v[94:97], v[176:179], v[144:147]
	v_mfma_f32_16x16x32_bf16 v[140:143], v[104:107], v[176:179], v[140:143]
	v_mfma_f32_16x16x32_bf16 v[124:127], v[94:97], v[184:187], v[124:127]
	v_mfma_f32_16x16x32_bf16 v[116:119], v[104:107], v[184:187], v[116:119]
	v_mfma_f32_16x16x32_bf16 v[78:81], v[94:97], v[192:195], v[78:81]
	v_mfma_f32_16x16x32_bf16 v[74:77], v[104:107], v[192:195], v[74:77]
	s_setprio 0
	s_setprio 1
	v_mfma_f32_16x16x32_bf16 v[152:155], v[108:111], v[164:167], v[152:155]
	v_mfma_f32_16x16x32_bf16 v[148:151], v[120:123], v[164:167], v[148:151]
	v_mfma_f32_16x16x32_bf16 v[136:139], v[108:111], v[172:175], v[136:139]
	v_mfma_f32_16x16x32_bf16 v[132:135], v[120:123], v[172:175], v[132:135]
	v_mfma_f32_16x16x32_bf16 v[86:89], v[108:111], v[180:183], v[86:89]
	v_mfma_f32_16x16x32_bf16 v[82:85], v[120:123], v[180:183], v[82:85]
	v_mfma_f32_16x16x32_bf16 v[70:73], v[108:111], v[188:191], v[70:73]
	v_mfma_f32_16x16x32_bf16 v[66:69], v[120:123], v[188:191], v[66:69]
	v_mfma_f32_16x16x32_bf16 v[152:155], v[112:115], v[168:171], v[152:155]
	v_mfma_f32_16x16x32_bf16 v[148:151], v[128:131], v[168:171], v[148:151]
	v_mfma_f32_16x16x32_bf16 v[136:139], v[112:115], v[176:179], v[136:139]
	v_mfma_f32_16x16x32_bf16 v[132:135], v[128:131], v[176:179], v[132:135]
	v_mfma_f32_16x16x32_bf16 v[86:89], v[112:115], v[184:187], v[86:89]
	v_mfma_f32_16x16x32_bf16 v[82:85], v[128:131], v[184:187], v[82:85]
	v_mfma_f32_16x16x32_bf16 v[70:73], v[112:115], v[192:195], v[70:73]
	v_mfma_f32_16x16x32_bf16 v[66:69], v[128:131], v[192:195], v[66:69]
	s_setprio 0
	s_barrier
	s_add_i32 s4, s6, s91
	v_lshl_add_u64 v[200:201], v[200:201], 0, s[42:43]
	s_mov_b32 m0, s4
	ds_read_b128 v[164:167], v241 offset:49152
	ds_read_b128 v[168:171], v241 offset:50176
	ds_read_b128 v[172:175], v241 offset:51200
	ds_read_b128 v[176:179], v241 offset:52224
	ds_read_b128 v[180:183], v241 offset:53248
	ds_read_b128 v[184:187], v241 offset:54272
	ds_read_b128 v[188:191], v241 offset:55296
	ds_read_b128 v[192:195], v241 offset:56320
	global_load_lds_dwordx4 v[200:201], off
	s_add_i32 m0, s4, 0x2000
	s_add_u32 s4, s70, 0x40080
	v_lshl_add_u64 v[200:201], v[202:203], 0, s[42:43]
	s_addc_u32 s5, s71, 0
	s_add_i32 s6, s7, s91
	global_load_lds_dwordx4 v[200:201], off
	v_lshl_add_u64 v[200:201], s[4:5], 0, v[204:205]
	s_mov_b32 m0, s6
	s_nop 0
	global_load_lds_dwordx4 v[200:201], off
	v_lshl_add_u64 v[200:201], s[4:5], 0, v[208:209]
	s_add_i32 m0, s6, 0x2000
	s_nop 0
	global_load_lds_dwordx4 v[200:201], off
	v_lshl_add_u64 v[200:201], v[210:211], 0, s[42:43]
	s_add_i32 m0, s44, 0x8000
	s_nop 0
	global_load_lds_dwordx4 v[200:201], off
	v_lshl_add_u64 v[200:201], v[212:213], 0, s[42:43]
	s_add_i32 m0, s44, 0xa000
	s_nop 0
	global_load_lds_dwordx4 v[200:201], off
	s_waitcnt vmcnt(8)
	s_waitcnt lgkmcnt(0)
	s_setprio 1
	s_barrier
	v_mfma_f32_16x16x32_bf16 v[62:65], v[90:93], v[164:167], v[62:65]
	v_mfma_f32_16x16x32_bf16 v[58:61], v[100:103], v[164:167], v[58:61]
	v_mfma_f32_16x16x32_bf16 v[46:49], v[90:93], v[172:175], v[46:49]
	v_mfma_f32_16x16x32_bf16 v[42:45], v[100:103], v[172:175], v[42:45]
	v_mfma_f32_16x16x32_bf16 v[30:33], v[90:93], v[180:183], v[30:33]
	v_mfma_f32_16x16x32_bf16 v[26:29], v[100:103], v[180:183], v[26:29]
	v_mfma_f32_16x16x32_bf16 v[14:17], v[90:93], v[188:191], v[14:17]
	v_mfma_f32_16x16x32_bf16 v[10:13], v[100:103], v[188:191], v[10:13]
	v_mfma_f32_16x16x32_bf16 v[62:65], v[94:97], v[168:171], v[62:65]
	v_mfma_f32_16x16x32_bf16 v[58:61], v[104:107], v[168:171], v[58:61]
	v_mfma_f32_16x16x32_bf16 v[46:49], v[94:97], v[176:179], v[46:49]
	v_mfma_f32_16x16x32_bf16 v[42:45], v[104:107], v[176:179], v[42:45]
	v_mfma_f32_16x16x32_bf16 v[30:33], v[94:97], v[184:187], v[30:33]
	v_mfma_f32_16x16x32_bf16 v[26:29], v[104:107], v[184:187], v[26:29]
	v_mfma_f32_16x16x32_bf16 v[14:17], v[94:97], v[192:195], v[14:17]
	v_mfma_f32_16x16x32_bf16 v[10:13], v[104:107], v[192:195], v[10:13]
	s_setprio 0
	s_setprio 1
	v_mfma_f32_16x16x32_bf16 v[54:57], v[108:111], v[164:167], v[54:57]
	v_mfma_f32_16x16x32_bf16 v[50:53], v[120:123], v[164:167], v[50:53]
	v_mfma_f32_16x16x32_bf16 v[38:41], v[108:111], v[172:175], v[38:41]
	v_mfma_f32_16x16x32_bf16 v[34:37], v[120:123], v[172:175], v[34:37]
	v_mfma_f32_16x16x32_bf16 v[22:25], v[108:111], v[180:183], v[22:25]
	v_mfma_f32_16x16x32_bf16 v[18:21], v[120:123], v[180:183], v[18:21]
	v_mfma_f32_16x16x32_bf16 v[6:9], v[108:111], v[188:191], v[6:9]
	v_mfma_f32_16x16x32_bf16 v[2:5], v[120:123], v[188:191], v[2:5]
	v_mfma_f32_16x16x32_bf16 v[54:57], v[112:115], v[168:171], v[54:57]
	v_mfma_f32_16x16x32_bf16 v[50:53], v[128:131], v[168:171], v[50:53]
	v_mfma_f32_16x16x32_bf16 v[38:41], v[112:115], v[176:179], v[38:41]
	v_mfma_f32_16x16x32_bf16 v[34:37], v[128:131], v[176:179], v[34:37]
	v_mfma_f32_16x16x32_bf16 v[22:25], v[112:115], v[184:187], v[22:25]
	v_mfma_f32_16x16x32_bf16 v[18:21], v[128:131], v[184:187], v[18:21]
	v_mfma_f32_16x16x32_bf16 v[6:9], v[112:115], v[192:195], v[6:9]
	v_mfma_f32_16x16x32_bf16 v[2:5], v[128:131], v[192:195], v[2:5]
	s_setprio 0
	s_barrier
	s_mov_b32 s100, 0
	s_add_i32 s97, s97, 2
	s_add_u32 s68, s68, 0x100
	s_addc_u32 s69, s69, 0
	s_add_u32 vcc_hi, vcc_hi, 0x100
	s_addc_u32 s96, s96, 0
	s_cmp_gt_u32 s97, 13
	s_cbranch_scc0 .LBB0_864
	s_mov_b32 s100, 1
	s_and_b64 vcc, exec, s[12:13]
	s_cbranch_vccz .LBB0_867
	s_barrier
	s_setprio 1

.LBB0_886:
	s_setprio 0
	s_waitcnt vmcnt(0)
	v_readlane_b32 s70, v255, 37
	v_readlane_b32 s71, v255, 38
	s_mov_b64 s[92:93], s[10:11]
	s_barrier

.Lmy_sk6:
	s_waitcnt lgkmcnt(0)
	s_setprio 1
	s_barrier
	v_mfma_f32_16x16x32_bf16 v[62:65], v[86:89], v[164:167], v[62:65]
	v_mfma_f32_16x16x32_bf16 v[58:61], v[100:103], v[164:167], v[58:61]
	v_mfma_f32_16x16x32_bf16 v[46:49], v[86:89], v[172:175], v[46:49]
	v_mfma_f32_16x16x32_bf16 v[42:45], v[100:103], v[172:175], v[42:45]
	v_mfma_f32_16x16x32_bf16 v[30:33], v[86:89], v[180:183], v[30:33]
	v_mfma_f32_16x16x32_bf16 v[26:29], v[100:103], v[180:183], v[26:29]
	v_mfma_f32_16x16x32_bf16 v[14:17], v[86:89], v[188:191], v[14:17]
	v_mfma_f32_16x16x32_bf16 v[10:13], v[100:103], v[188:191], v[10:13]
	v_mfma_f32_16x16x32_bf16 v[62:65], v[90:93], v[168:171], v[62:65]
	v_mfma_f32_16x16x32_bf16 v[58:61], v[104:107], v[168:171], v[58:61]
	v_mfma_f32_16x16x32_bf16 v[46:49], v[90:93], v[176:179], v[46:49]
	v_mfma_f32_16x16x32_bf16 v[42:45], v[104:107], v[176:179], v[42:45]
	v_mfma_f32_16x16x32_bf16 v[30:33], v[90:93], v[184:187], v[30:33]
	v_mfma_f32_16x16x32_bf16 v[26:29], v[104:107], v[184:187], v[26:29]
	v_mfma_f32_16x16x32_bf16 v[14:17], v[90:93], v[192:195], v[14:17]
	v_mfma_f32_16x16x32_bf16 v[10:13], v[104:107], v[192:195], v[10:13]
	s_setprio 0
	s_setprio 1
	v_mfma_f32_16x16x32_bf16 v[54:57], v[108:111], v[164:167], v[54:57]
	v_mfma_f32_16x16x32_bf16 v[50:53], v[116:119], v[164:167], v[50:53]
	v_mfma_f32_16x16x32_bf16 v[38:41], v[108:111], v[172:175], v[38:41]
	v_mfma_f32_16x16x32_bf16 v[34:37], v[116:119], v[172:175], v[34:37]
	v_mfma_f32_16x16x32_bf16 v[22:25], v[108:111], v[180:183], v[22:25]
	v_mfma_f32_16x16x32_bf16 v[18:21], v[116:119], v[180:183], v[18:21]
	v_mfma_f32_16x16x32_bf16 v[6:9], v[108:111], v[188:191], v[6:9]
	v_mfma_f32_16x16x32_bf16 v[2:5], v[116:119], v[188:191], v[2:5]
	v_mfma_f32_16x16x32_bf16 v[54:57], v[112:115], v[168:171], v[54:57]
	v_mfma_f32_16x16x32_bf16 v[50:53], v[124:127], v[168:171], v[50:53]
	v_mfma_f32_16x16x32_bf16 v[38:41], v[112:115], v[176:179], v[38:41]
	v_mfma_f32_16x16x32_bf16 v[34:37], v[124:127], v[176:179], v[34:37]
	v_mfma_f32_16x16x32_bf16 v[22:25], v[112:115], v[184:187], v[22:25]
	v_mfma_f32_16x16x32_bf16 v[18:21], v[124:127], v[184:187], v[18:21]
	v_mfma_f32_16x16x32_bf16 v[6:9], v[112:115], v[192:195], v[6:9]
	v_mfma_f32_16x16x32_bf16 v[2:5], v[124:127], v[192:195], v[2:5]
	s_setprio 0
	s_barrier
	s_add_i32 s45, 0, 0x18000
	s_add_i32 s97, 0, 0x1c000
	v_add_u32_e32 v104, s45, v223
	v_add_u32_e32 v124, s97, v223
	ds_read_b128 v[86:89], v104
	ds_read_b128 v[90:93], v104 offset:1024
	ds_read_b128 v[100:103], v104 offset:2048
	ds_read_b128 v[104:107], v104 offset:3072
	ds_read_b128 v[108:111], v124
	ds_read_b128 v[112:115], v124 offset:1024
	ds_read_b128 v[116:119], v124 offset:2048
	ds_read_b128 v[124:127], v124 offset:3072
	s_add_u32 s4, s70, 0x40000
	s_addc_u32 s5, s71, 0
	v_lshl_add_u64 v[214:215], s[4:5], 0, v[98:99]
	s_add_i32 m0, s44, 0x4000
	ds_read_b128 v[164:167], v225 offset:32768
	ds_read_b128 v[168:171], v225 offset:33792
	ds_read_b128 v[172:175], v225 offset:34816
	ds_read_b128 v[176:179], v225 offset:35840
	ds_read_b128 v[180:183], v225 offset:36864
	ds_read_b128 v[184:187], v225 offset:37888
	ds_read_b128 v[188:191], v225 offset:38912
	ds_read_b128 v[192:195], v225 offset:39936
	global_load_lds_dwordx4 v[214:215], off
	v_lshl_add_u64 v[214:215], s[4:5], 0, v[206:207]
	s_add_i32 m0, s44, 0x6000
	s_nop 0
	global_load_lds_dwordx4 v[214:215], off
	s_waitcnt vmcnt(8)
	s_waitcnt lgkmcnt(0)
	s_setprio 1
	s_barrier
	v_mfma_f32_16x16x32_bf16 v[160:163], v[86:89], v[164:167], v[160:163]
	v_mfma_f32_16x16x32_bf16 v[156:159], v[100:103], v[164:167], v[156:159]
	v_mfma_f32_16x16x32_bf16 v[144:147], v[86:89], v[172:175], v[144:147]
	v_mfma_f32_16x16x32_bf16 v[140:143], v[100:103], v[172:175], v[140:143]
	v_mfma_f32_16x16x32_bf16 v[128:131], v[86:89], v[180:183], v[128:131]
	v_mfma_f32_16x16x32_bf16 v[120:123], v[100:103], v[180:183], v[120:123]
	v_mfma_f32_16x16x32_bf16 v[78:81], v[86:89], v[188:191], v[78:81]
	v_mfma_f32_16x16x32_bf16 v[74:77], v[100:103], v[188:191], v[74:77]
	v_mfma_f32_16x16x32_bf16 v[160:163], v[90:93], v[168:171], v[160:163]
	v_mfma_f32_16x16x32_bf16 v[156:159], v[104:107], v[168:171], v[156:159]
	v_mfma_f32_16x16x32_bf16 v[144:147], v[90:93], v[176:179], v[144:147]
	v_mfma_f32_16x16x32_bf16 v[140:143], v[104:107], v[176:179], v[140:143]
	v_mfma_f32_16x16x32_bf16 v[128:131], v[90:93], v[184:187], v[128:131]
	v_mfma_f32_16x16x32_bf16 v[120:123], v[104:107], v[184:187], v[120:123]
	v_mfma_f32_16x16x32_bf16 v[78:81], v[90:93], v[192:195], v[78:81]
	v_mfma_f32_16x16x32_bf16 v[74:77], v[104:107], v[192:195], v[74:77]
	s_setprio 0
	s_setprio 1
	v_mfma_f32_16x16x32_bf16 v[152:155], v[108:111], v[164:167], v[152:155]
	v_mfma_f32_16x16x32_bf16 v[148:151], v[116:119], v[164:167], v[148:151]
	v_mfma_f32_16x16x32_bf16 v[136:139], v[108:111], v[172:175], v[136:139]
	v_mfma_f32_16x16x32_bf16 v[132:135], v[116:119], v[172:175], v[132:135]
	v_mfma_f32_16x16x32_bf16 v[94:97], v[108:111], v[180:183], v[94:97]
	v_mfma_f32_16x16x32_bf16 v[82:85], v[116:119], v[180:183], v[82:85]
	v_mfma_f32_16x16x32_bf16 v[70:73], v[108:111], v[188:191], v[70:73]
	v_mfma_f32_16x16x32_bf16 v[66:69], v[116:119], v[188:191], v[66:69]
	v_mfma_f32_16x16x32_bf16 v[152:155], v[112:115], v[168:171], v[152:155]
	v_mfma_f32_16x16x32_bf16 v[148:151], v[124:127], v[168:171], v[148:151]
	v_mfma_f32_16x16x32_bf16 v[136:139], v[112:115], v[176:179], v[136:139]
	v_mfma_f32_16x16x32_bf16 v[132:135], v[124:127], v[176:179], v[132:135]
	v_mfma_f32_16x16x32_bf16 v[94:97], v[112:115], v[184:187], v[94:97]
	v_mfma_f32_16x16x32_bf16 v[82:85], v[124:127], v[184:187], v[82:85]
	v_mfma_f32_16x16x32_bf16 v[70:73], v[112:115], v[192:195], v[70:73]
	v_mfma_f32_16x16x32_bf16 v[66:69], v[124:127], v[192:195], v[66:69]
	s_setprio 0
	s_barrier
	s_add_i32 s4, s45, s74
	v_lshl_add_u64 v[200:201], v[200:201], 0, s[42:43]
	s_mov_b32 m0, s4
	ds_read_b128 v[164:167], v225 offset:49152
	ds_read_b128 v[168:171], v225 offset:50176
	ds_read_b128 v[172:175], v225 offset:51200
	ds_read_b128 v[176:179], v225 offset:52224
	ds_read_b128 v[180:183], v225 offset:53248
	ds_read_b128 v[184:187], v225 offset:54272
	ds_read_b128 v[188:191], v225 offset:55296
	ds_read_b128 v[192:195], v225 offset:56320
	global_load_lds_dwordx4 v[200:201], off
	s_add_i32 m0, s4, 0x2000
	s_add_u32 s4, s68, 0x40080
	v_lshl_add_u64 v[200:201], v[202:203], 0, s[42:43]
	s_addc_u32 s5, s69, 0
	s_add_i32 s45, s97, s74
	global_load_lds_dwordx4 v[200:201], off
	v_lshl_add_u64 v[200:201], s[4:5], 0, v[204:205]
	s_mov_b32 m0, s45
	s_nop 0
	global_load_lds_dwordx4 v[200:201], off
	v_lshl_add_u64 v[200:201], s[4:5], 0, v[208:209]
	s_add_i32 m0, s45, 0x2000
	s_nop 0
	global_load_lds_dwordx4 v[200:201], off
	v_lshl_add_u64 v[200:201], v[210:211], 0, s[42:43]
	s_add_i32 m0, s44, 0x8000
	s_nop 0
	global_load_lds_dwordx4 v[200:201], off
	v_lshl_add_u64 v[200:201], v[212:213], 0, s[42:43]
	s_add_i32 m0, s44, 0xa000
	s_nop 0
	global_load_lds_dwordx4 v[200:201], off
	s_waitcnt vmcnt(8)
	s_waitcnt lgkmcnt(0)
	s_setprio 1
	s_barrier
	v_mfma_f32_16x16x32_bf16 v[62:65], v[86:89], v[164:167], v[62:65]
	v_mfma_f32_16x16x32_bf16 v[58:61], v[100:103], v[164:167], v[58:61]
	v_mfma_f32_16x16x32_bf16 v[46:49], v[86:89], v[172:175], v[46:49]
	v_mfma_f32_16x16x32_bf16 v[42:45], v[100:103], v[172:175], v[42:45]
	v_mfma_f32_16x16x32_bf16 v[30:33], v[86:89], v[180:183], v[30:33]
	v_mfma_f32_16x16x32_bf16 v[26:29], v[100:103], v[180:183], v[26:29]
	v_mfma_f32_16x16x32_bf16 v[14:17], v[86:89], v[188:191], v[14:17]
	v_mfma_f32_16x16x32_bf16 v[10:13], v[100:103], v[188:191], v[10:13]
	v_mfma_f32_16x16x32_bf16 v[62:65], v[90:93], v[168:171], v[62:65]
	v_mfma_f32_16x16x32_bf16 v[58:61], v[104:107], v[168:171], v[58:61]
	v_mfma_f32_16x16x32_bf16 v[46:49], v[90:93], v[176:179], v[46:49]
	v_mfma_f32_16x16x32_bf16 v[42:45], v[104:107], v[176:179], v[42:45]
	v_mfma_f32_16x16x32_bf16 v[30:33], v[90:93], v[184:187], v[30:33]
	v_mfma_f32_16x16x32_bf16 v[26:29], v[104:107], v[184:187], v[26:29]
	v_mfma_f32_16x16x32_bf16 v[14:17], v[90:93], v[192:195], v[14:17]
	v_mfma_f32_16x16x32_bf16 v[10:13], v[104:107], v[192:195], v[10:13]
	s_setprio 0
	s_setprio 1
	v_mfma_f32_16x16x32_bf16 v[54:57], v[108:111], v[164:167], v[54:57]
	v_mfma_f32_16x16x32_bf16 v[50:53], v[116:119], v[164:167], v[50:53]
	v_mfma_f32_16x16x32_bf16 v[38:41], v[108:111], v[172:175], v[38:41]
	v_mfma_f32_16x16x32_bf16 v[34:37], v[116:119], v[172:175], v[34:37]
	v_mfma_f32_16x16x32_bf16 v[22:25], v[108:111], v[180:183], v[22:25]
	v_mfma_f32_16x16x32_bf16 v[18:21], v[116:119], v[180:183], v[18:21]
	v_mfma_f32_16x16x32_bf16 v[6:9], v[108:111], v[188:191], v[6:9]
	v_mfma_f32_16x16x32_bf16 v[2:5], v[116:119], v[188:191], v[2:5]
	v_mfma_f32_16x16x32_bf16 v[54:57], v[112:115], v[168:171], v[54:57]
	v_mfma_f32_16x16x32_bf16 v[50:53], v[124:127], v[168:171], v[50:53]
	v_mfma_f32_16x16x32_bf16 v[38:41], v[112:115], v[176:179], v[38:41]
	v_mfma_f32_16x16x32_bf16 v[34:37], v[124:127], v[176:179], v[34:37]
	v_mfma_f32_16x16x32_bf16 v[22:25], v[112:115], v[184:187], v[22:25]
	v_mfma_f32_16x16x32_bf16 v[18:21], v[124:127], v[184:187], v[18:21]
	v_mfma_f32_16x16x32_bf16 v[6:9], v[112:115], v[192:195], v[6:9]
	v_mfma_f32_16x16x32_bf16 v[2:5], v[124:127], v[192:195], v[2:5]
	s_setprio 0
	s_barrier
	s_mov_b32 s100, 0
	s_add_i32 s96, s96, 2
	s_add_u32 s56, s56, 0x100
	s_addc_u32 s57, s57, 0
	s_add_u32 s95, s95, 0x100
	s_addc_u32 vcc_lo, vcc_lo, 0
	s_cmp_gt_u32 s96, 13
	s_cbranch_scc0 .LBB0_908
	s_mov_b32 s100, 1
	v_mov_b32_e32 v196, 0x2d00
	v_mov_b32_e32 v231, 0x2400
	v_mov_b32_e32 v228, 0x1b00
	s_and_b64 vcc, exec, s[0:1]
	s_movk_i32 s21, 0x4000
	s_cbranch_vccz .LBB0_911
	s_barrier
	s_setprio 1

.LBB0_930:
	s_setprio 0
	s_waitcnt vmcnt(0)
	v_readlane_b32 s52, v252, 36
	v_readlane_b32 s8, v255, 31
	v_readlane_b32 s74, v255, 33
	v_readlane_b32 s16, v255, 42
	v_readlane_b32 s53, v252, 37
	v_readlane_b32 s9, v255, 32
	v_readlane_b32 s75, v255, 34
	v_readlane_b32 s17, v255, 43
	s_barrier

.Lmy_sk8:
	s_waitcnt lgkmcnt(0)
	s_setprio 1
	s_barrier
	v_mfma_f32_16x16x32_bf16 v[62:65], v[132:135], v[204:207], v[62:65]
	v_mfma_f32_16x16x32_bf16 v[58:61], v[140:143], v[204:207], v[58:61]
	v_mfma_f32_16x16x32_bf16 v[46:49], v[132:135], v[212:215], v[46:49]
	v_mfma_f32_16x16x32_bf16 v[42:45], v[140:143], v[212:215], v[42:45]
	v_mfma_f32_16x16x32_bf16 v[30:33], v[132:135], v[220:223], v[30:33]
	v_mfma_f32_16x16x32_bf16 v[26:29], v[140:143], v[220:223], v[26:29]
	v_mfma_f32_16x16x32_bf16 v[14:17], v[132:135], v[238:241], v[14:17]
	v_mfma_f32_16x16x32_bf16 v[10:13], v[140:143], v[238:241], v[10:13]
	v_mfma_f32_16x16x32_bf16 v[62:65], v[136:139], v[208:211], v[62:65]
	v_mfma_f32_16x16x32_bf16 v[58:61], v[144:147], v[208:211], v[58:61]
	v_mfma_f32_16x16x32_bf16 v[46:49], v[136:139], v[216:219], v[46:49]
	v_mfma_f32_16x16x32_bf16 v[42:45], v[144:147], v[216:219], v[42:45]
	v_mfma_f32_16x16x32_bf16 v[30:33], v[136:139], v[224:227], v[30:33]
	v_mfma_f32_16x16x32_bf16 v[26:29], v[144:147], v[224:227], v[26:29]
	v_mfma_f32_16x16x32_bf16 v[14:17], v[136:139], v[242:245], v[14:17]
	v_mfma_f32_16x16x32_bf16 v[10:13], v[144:147], v[242:245], v[10:13]
	s_setprio 0
	s_setprio 1
	v_mfma_f32_16x16x32_bf16 v[54:57], v[156:159], v[204:207], v[54:57]
	v_mfma_f32_16x16x32_bf16 v[50:53], v[192:195], v[204:207], v[50:53]
	v_mfma_f32_16x16x32_bf16 v[38:41], v[156:159], v[212:215], v[38:41]
	v_mfma_f32_16x16x32_bf16 v[34:37], v[192:195], v[212:215], v[34:37]
	v_mfma_f32_16x16x32_bf16 v[22:25], v[156:159], v[220:223], v[22:25]
	v_mfma_f32_16x16x32_bf16 v[18:21], v[192:195], v[220:223], v[18:21]
	v_mfma_f32_16x16x32_bf16 v[6:9], v[156:159], v[238:241], v[6:9]
	v_mfma_f32_16x16x32_bf16 v[2:5], v[192:195], v[238:241], v[2:5]
	v_mfma_f32_16x16x32_bf16 v[54:57], v[162:165], v[208:211], v[54:57]
	v_mfma_f32_16x16x32_bf16 v[50:53], v[200:203], v[208:211], v[50:53]
	v_mfma_f32_16x16x32_bf16 v[38:41], v[162:165], v[216:219], v[38:41]
	v_mfma_f32_16x16x32_bf16 v[34:37], v[200:203], v[216:219], v[34:37]
	v_mfma_f32_16x16x32_bf16 v[22:25], v[162:165], v[224:227], v[22:25]
	v_mfma_f32_16x16x32_bf16 v[18:21], v[200:203], v[224:227], v[18:21]
	v_mfma_f32_16x16x32_bf16 v[6:9], v[162:165], v[242:245], v[6:9]
	v_mfma_f32_16x16x32_bf16 v[2:5], v[200:203], v[242:245], v[2:5]
	s_setprio 0
	s_barrier
	s_add_i32 s6, 0, 0x18000
	s_add_i32 s7, 0, 0x1c000
	v_add_u32_e32 v144, s6, v189
	v_add_u32_e32 v160, s7, v189
	ds_read_b128 v[132:135], v144
	ds_read_b128 v[136:139], v144 offset:1024
	ds_read_b128 v[140:143], v144 offset:2048
	ds_read_b128 v[144:147], v144 offset:3072
	ds_read_b128 v[156:159], v160
	ds_read_b128 v[162:165], v160 offset:1024
	ds_read_b128 v[192:195], v160 offset:2048
	ds_read_b128 v[200:203], v160 offset:3072
	s_add_u32 s4, s68, 0x40000
	s_addc_u32 s5, s69, 0
	v_lshl_add_u64 v[246:247], s[4:5], 0, v[98:99]
	s_add_i32 m0, s44, 0x4000
	ds_read_b128 v[204:207], v191 offset:32768
	ds_read_b128 v[208:211], v191 offset:33792
	ds_read_b128 v[212:215], v191 offset:34816
	ds_read_b128 v[216:219], v191 offset:35840
	ds_read_b128 v[220:223], v191 offset:36864
	ds_read_b128 v[224:227], v191 offset:37888
	ds_read_b128 v[238:241], v191 offset:38912
	ds_read_b128 v[242:245], v191 offset:39936
	global_load_lds_dwordx4 v[246:247], off
	v_lshl_add_u64 v[246:247], s[4:5], 0, v[150:151]
	s_add_i32 m0, s44, 0x6000
	s_nop 0
	global_load_lds_dwordx4 v[246:247], off
	s_waitcnt vmcnt(8)
	s_waitcnt lgkmcnt(0)
	s_setprio 1
	s_barrier
	v_mfma_f32_16x16x32_bf16 v[128:131], v[132:135], v[204:207], v[128:131]
	v_mfma_f32_16x16x32_bf16 v[124:127], v[140:143], v[204:207], v[124:127]
	v_mfma_f32_16x16x32_bf16 v[112:115], v[132:135], v[212:215], v[112:115]
	v_mfma_f32_16x16x32_bf16 v[108:111], v[140:143], v[212:215], v[108:111]
	v_mfma_f32_16x16x32_bf16 v[94:97], v[132:135], v[220:223], v[94:97]
	v_mfma_f32_16x16x32_bf16 v[90:93], v[140:143], v[220:223], v[90:93]
	v_mfma_f32_16x16x32_bf16 v[78:81], v[132:135], v[238:241], v[78:81]
	v_mfma_f32_16x16x32_bf16 v[74:77], v[140:143], v[238:241], v[74:77]
	v_mfma_f32_16x16x32_bf16 v[128:131], v[136:139], v[208:211], v[128:131]
	v_mfma_f32_16x16x32_bf16 v[124:127], v[144:147], v[208:211], v[124:127]
	v_mfma_f32_16x16x32_bf16 v[112:115], v[136:139], v[216:219], v[112:115]
	v_mfma_f32_16x16x32_bf16 v[108:111], v[144:147], v[216:219], v[108:111]
	v_mfma_f32_16x16x32_bf16 v[94:97], v[136:139], v[224:227], v[94:97]
	v_mfma_f32_16x16x32_bf16 v[90:93], v[144:147], v[224:227], v[90:93]
	v_mfma_f32_16x16x32_bf16 v[78:81], v[136:139], v[242:245], v[78:81]
	v_mfma_f32_16x16x32_bf16 v[74:77], v[144:147], v[242:245], v[74:77]
	s_setprio 0
	s_setprio 1
	v_mfma_f32_16x16x32_bf16 v[120:123], v[156:159], v[204:207], v[120:123]
	v_mfma_f32_16x16x32_bf16 v[116:119], v[192:195], v[204:207], v[116:119]
	v_mfma_f32_16x16x32_bf16 v[104:107], v[156:159], v[212:215], v[104:107]
	v_mfma_f32_16x16x32_bf16 v[100:103], v[192:195], v[212:215], v[100:103]
	v_mfma_f32_16x16x32_bf16 v[86:89], v[156:159], v[220:223], v[86:89]
	v_mfma_f32_16x16x32_bf16 v[82:85], v[192:195], v[220:223], v[82:85]
	v_mfma_f32_16x16x32_bf16 v[70:73], v[156:159], v[238:241], v[70:73]
	v_mfma_f32_16x16x32_bf16 v[66:69], v[192:195], v[238:241], v[66:69]
	v_mfma_f32_16x16x32_bf16 v[120:123], v[162:165], v[208:211], v[120:123]
	v_mfma_f32_16x16x32_bf16 v[116:119], v[200:203], v[208:211], v[116:119]
	v_mfma_f32_16x16x32_bf16 v[104:107], v[162:165], v[216:219], v[104:107]
	v_mfma_f32_16x16x32_bf16 v[100:103], v[200:203], v[216:219], v[100:103]
	v_mfma_f32_16x16x32_bf16 v[86:89], v[162:165], v[224:227], v[86:89]
	v_mfma_f32_16x16x32_bf16 v[82:85], v[200:203], v[224:227], v[82:85]
	v_mfma_f32_16x16x32_bf16 v[70:73], v[162:165], v[242:245], v[70:73]
	v_mfma_f32_16x16x32_bf16 v[66:69], v[200:203], v[242:245], v[66:69]
	s_setprio 0
	s_barrier
	s_add_i32 s4, s6, s70
	v_lshl_add_u64 v[166:167], v[166:167], 0, s[42:43]
	s_mov_b32 m0, s4
	ds_read_b128 v[204:207], v191 offset:49152
	ds_read_b128 v[208:211], v191 offset:50176
	ds_read_b128 v[212:215], v191 offset:51200
	ds_read_b128 v[216:219], v191 offset:52224
	ds_read_b128 v[220:223], v191 offset:53248
	ds_read_b128 v[224:227], v191 offset:54272
	ds_read_b128 v[238:241], v191 offset:55296
	ds_read_b128 v[242:245], v191 offset:56320
	global_load_lds_dwordx4 v[166:167], off
	s_add_i32 m0, s4, 0x2000
	s_add_u32 s4, s56, 0x40080
	v_lshl_add_u64 v[166:167], v[170:171], 0, s[42:43]
	s_addc_u32 s5, s57, 0
	s_add_i32 s6, s7, s70
	global_load_lds_dwordx4 v[166:167], off
	v_lshl_add_u64 v[166:167], s[4:5], 0, v[148:149]
	s_mov_b32 m0, s6
	s_nop 0
	global_load_lds_dwordx4 v[166:167], off
	v_lshl_add_u64 v[166:167], s[4:5], 0, v[152:153]
	s_add_i32 m0, s6, 0x2000
	s_nop 0
	global_load_lds_dwordx4 v[166:167], off
	v_lshl_add_u64 v[166:167], v[176:177], 0, s[42:43]
	s_add_i32 m0, s44, 0x8000
	s_nop 0
	global_load_lds_dwordx4 v[166:167], off
	v_lshl_add_u64 v[166:167], v[180:181], 0, s[42:43]
	s_add_i32 m0, s44, 0xa000
	s_nop 0
	global_load_lds_dwordx4 v[166:167], off
	s_waitcnt vmcnt(8)
	s_waitcnt lgkmcnt(0)
	s_setprio 1
	s_barrier
	v_mfma_f32_16x16x32_bf16 v[62:65], v[132:135], v[204:207], v[62:65]
	v_mfma_f32_16x16x32_bf16 v[58:61], v[140:143], v[204:207], v[58:61]
	v_mfma_f32_16x16x32_bf16 v[46:49], v[132:135], v[212:215], v[46:49]
	v_mfma_f32_16x16x32_bf16 v[42:45], v[140:143], v[212:215], v[42:45]
	v_mfma_f32_16x16x32_bf16 v[30:33], v[132:135], v[220:223], v[30:33]
	v_mfma_f32_16x16x32_bf16 v[26:29], v[140:143], v[220:223], v[26:29]
	v_mfma_f32_16x16x32_bf16 v[14:17], v[132:135], v[238:241], v[14:17]
	v_mfma_f32_16x16x32_bf16 v[10:13], v[140:143], v[238:241], v[10:13]
	v_mfma_f32_16x16x32_bf16 v[62:65], v[136:139], v[208:211], v[62:65]
	v_mfma_f32_16x16x32_bf16 v[58:61], v[144:147], v[208:211], v[58:61]
	v_mfma_f32_16x16x32_bf16 v[46:49], v[136:139], v[216:219], v[46:49]
	v_mfma_f32_16x16x32_bf16 v[42:45], v[144:147], v[216:219], v[42:45]
	v_mfma_f32_16x16x32_bf16 v[30:33], v[136:139], v[224:227], v[30:33]
	v_mfma_f32_16x16x32_bf16 v[26:29], v[144:147], v[224:227], v[26:29]
	v_mfma_f32_16x16x32_bf16 v[14:17], v[136:139], v[242:245], v[14:17]
	v_mfma_f32_16x16x32_bf16 v[10:13], v[144:147], v[242:245], v[10:13]
	s_setprio 0
	s_setprio 1
	v_mfma_f32_16x16x32_bf16 v[54:57], v[156:159], v[204:207], v[54:57]
	v_mfma_f32_16x16x32_bf16 v[50:53], v[192:195], v[204:207], v[50:53]
	v_mfma_f32_16x16x32_bf16 v[38:41], v[156:159], v[212:215], v[38:41]
	v_mfma_f32_16x16x32_bf16 v[34:37], v[192:195], v[212:215], v[34:37]
	v_mfma_f32_16x16x32_bf16 v[22:25], v[156:159], v[220:223], v[22:25]
	v_mfma_f32_16x16x32_bf16 v[18:21], v[192:195], v[220:223], v[18:21]
	v_mfma_f32_16x16x32_bf16 v[6:9], v[156:159], v[238:241], v[6:9]
	v_mfma_f32_16x16x32_bf16 v[2:5], v[192:195], v[238:241], v[2:5]
	v_mfma_f32_16x16x32_bf16 v[54:57], v[162:165], v[208:211], v[54:57]
	v_mfma_f32_16x16x32_bf16 v[50:53], v[200:203], v[208:211], v[50:53]
	v_mfma_f32_16x16x32_bf16 v[38:41], v[162:165], v[216:219], v[38:41]
	v_mfma_f32_16x16x32_bf16 v[34:37], v[200:203], v[216:219], v[34:37]
	v_mfma_f32_16x16x32_bf16 v[22:25], v[162:165], v[224:227], v[22:25]
	v_mfma_f32_16x16x32_bf16 v[18:21], v[200:203], v[224:227], v[18:21]
	v_mfma_f32_16x16x32_bf16 v[6:9], v[162:165], v[242:245], v[6:9]
	v_mfma_f32_16x16x32_bf16 v[2:5], v[200:203], v[242:245], v[2:5]
	s_setprio 0
	s_barrier
	s_mov_b32 s100, 0
	s_add_i32 s92, s92, 2
	s_add_u32 s40, s40, 0x100
	s_addc_u32 s41, s41, 0
	s_add_u32 s90, s90, 0x100
	s_addc_u32 s91, s91, 0
	s_cmp_gt_u32 s92, 13
	s_cbranch_scc0 .LBB0_1011
	s_mov_b32 s100, 1
	s_and_b64 vcc, exec, s[0:1]
	s_cbranch_vccz .LBB0_1014
	s_barrier
	s_setprio 1

.LBB0_1017:
	s_setprio 0
	s_waitcnt vmcnt(0)
	v_readlane_b32 s8, v255, 31
	v_readlane_b32 s74, v255, 33
	v_readlane_b32 s70, v255, 37
	v_readlane_b32 s9, v255, 32
	v_readlane_b32 s75, v255, 34
	v_readlane_b32 s77, v255, 36
	v_readlane_b32 s71, v255, 38
	s_barrier

.Lmy_sk10:
	s_waitcnt lgkmcnt(0)
	s_setprio 1
	s_barrier
	v_mfma_f32_16x16x32_bf16 v[62:65], v[112:115], v[164:167], v[62:65]
	v_mfma_f32_16x16x32_bf16 v[58:61], v[124:127], v[164:167], v[58:61]
	v_mfma_f32_16x16x32_bf16 v[46:49], v[112:115], v[178:181], v[46:49]
	v_mfma_f32_16x16x32_bf16 v[42:45], v[124:127], v[178:181], v[42:45]
	v_mfma_f32_16x16x32_bf16 v[30:33], v[112:115], v[186:189], v[30:33]
	v_mfma_f32_16x16x32_bf16 v[26:29], v[124:127], v[186:189], v[26:29]
	v_mfma_f32_16x16x32_bf16 v[14:17], v[112:115], v[200:203], v[14:17]
	v_mfma_f32_16x16x32_bf16 v[10:13], v[124:127], v[200:203], v[10:13]
	v_mfma_f32_16x16x32_bf16 v[62:65], v[116:119], v[168:171], v[62:65]
	v_mfma_f32_16x16x32_bf16 v[58:61], v[128:131], v[168:171], v[58:61]
	v_mfma_f32_16x16x32_bf16 v[46:49], v[116:119], v[182:185], v[46:49]
	v_mfma_f32_16x16x32_bf16 v[42:45], v[128:131], v[182:185], v[42:45]
	v_mfma_f32_16x16x32_bf16 v[30:33], v[116:119], v[190:193], v[30:33]
	v_mfma_f32_16x16x32_bf16 v[26:29], v[128:131], v[190:193], v[26:29]
	v_mfma_f32_16x16x32_bf16 v[14:17], v[116:119], v[208:211], v[14:17]
	v_mfma_f32_16x16x32_bf16 v[10:13], v[128:131], v[208:211], v[10:13]
	s_setprio 0
	s_setprio 1
	v_mfma_f32_16x16x32_bf16 v[54:57], v[148:151], v[164:167], v[54:57]
	v_mfma_f32_16x16x32_bf16 v[50:53], v[156:159], v[164:167], v[50:53]
	v_mfma_f32_16x16x32_bf16 v[38:41], v[148:151], v[178:181], v[38:41]
	v_mfma_f32_16x16x32_bf16 v[34:37], v[156:159], v[178:181], v[34:37]
	v_mfma_f32_16x16x32_bf16 v[22:25], v[148:151], v[186:189], v[22:25]
	v_mfma_f32_16x16x32_bf16 v[18:21], v[156:159], v[186:189], v[18:21]
	v_mfma_f32_16x16x32_bf16 v[6:9], v[148:151], v[200:203], v[6:9]
	v_mfma_f32_16x16x32_bf16 v[2:5], v[156:159], v[200:203], v[2:5]
	v_mfma_f32_16x16x32_bf16 v[54:57], v[152:155], v[168:171], v[54:57]
	v_mfma_f32_16x16x32_bf16 v[50:53], v[160:163], v[168:171], v[50:53]
	v_mfma_f32_16x16x32_bf16 v[38:41], v[152:155], v[182:185], v[38:41]
	v_mfma_f32_16x16x32_bf16 v[34:37], v[160:163], v[182:185], v[34:37]
	v_mfma_f32_16x16x32_bf16 v[22:25], v[152:155], v[190:193], v[22:25]
	v_mfma_f32_16x16x32_bf16 v[18:21], v[160:163], v[190:193], v[18:21]
	v_mfma_f32_16x16x32_bf16 v[6:9], v[152:155], v[208:211], v[6:9]
	v_mfma_f32_16x16x32_bf16 v[2:5], v[160:163], v[208:211], v[2:5]
	s_setprio 0
	s_barrier
	s_add_i32 s6, 0, 0x18000
	s_add_i32 s7, 0, 0x1c000
	v_add_u32_e32 v128, s6, v205
	v_add_u32_e32 v160, s7, v205
	ds_read_b128 v[112:115], v128
	ds_read_b128 v[116:119], v128 offset:1024
	ds_read_b128 v[124:127], v128 offset:2048
	ds_read_b128 v[128:131], v128 offset:3072
	ds_read_b128 v[148:151], v160
	ds_read_b128 v[152:155], v160 offset:1024
	ds_read_b128 v[156:159], v160 offset:2048
	ds_read_b128 v[160:163], v160 offset:3072
	s_add_u32 s4, vcc_lo, 0x100000
	s_addc_u32 s5, vcc_hi, 0
	v_lshl_add_u64 v[218:219], s[4:5], 0, v[98:99]
	s_add_i32 m0, s44, 0x4000
	ds_read_b128 v[164:167], v207 offset:32768
	ds_read_b128 v[168:171], v207 offset:33792
	ds_read_b128 v[178:181], v207 offset:34816
	ds_read_b128 v[182:185], v207 offset:35840
	ds_read_b128 v[186:189], v207 offset:36864
	ds_read_b128 v[190:193], v207 offset:37888
	ds_read_b128 v[200:203], v207 offset:38912
	ds_read_b128 v[208:211], v207 offset:39936
	global_load_lds_dwordx4 v[218:219], off
	v_lshl_add_u64 v[218:219], s[4:5], 0, v[174:175]
	s_add_i32 m0, s44, 0x6000
	s_nop 0
	global_load_lds_dwordx4 v[218:219], off
	s_waitcnt vmcnt(8)
	s_waitcnt lgkmcnt(0)
	s_setprio 1
	s_barrier
	v_mfma_f32_16x16x32_bf16 v[144:147], v[112:115], v[164:167], v[144:147]
	v_mfma_f32_16x16x32_bf16 v[140:143], v[124:127], v[164:167], v[140:143]
	v_mfma_f32_16x16x32_bf16 v[120:123], v[112:115], v[178:181], v[120:123]
	v_mfma_f32_16x16x32_bf16 v[108:111], v[124:127], v[178:181], v[108:111]
	v_mfma_f32_16x16x32_bf16 v[94:97], v[112:115], v[186:189], v[94:97]
	v_mfma_f32_16x16x32_bf16 v[90:93], v[124:127], v[186:189], v[90:93]
	v_mfma_f32_16x16x32_bf16 v[78:81], v[112:115], v[200:203], v[78:81]
	v_mfma_f32_16x16x32_bf16 v[74:77], v[124:127], v[200:203], v[74:77]
	v_mfma_f32_16x16x32_bf16 v[144:147], v[116:119], v[168:171], v[144:147]
	v_mfma_f32_16x16x32_bf16 v[140:143], v[128:131], v[168:171], v[140:143]
	v_mfma_f32_16x16x32_bf16 v[120:123], v[116:119], v[182:185], v[120:123]
	v_mfma_f32_16x16x32_bf16 v[108:111], v[128:131], v[182:185], v[108:111]
	v_mfma_f32_16x16x32_bf16 v[94:97], v[116:119], v[190:193], v[94:97]
	v_mfma_f32_16x16x32_bf16 v[90:93], v[128:131], v[190:193], v[90:93]
	v_mfma_f32_16x16x32_bf16 v[78:81], v[116:119], v[208:211], v[78:81]
	v_mfma_f32_16x16x32_bf16 v[74:77], v[128:131], v[208:211], v[74:77]
	s_setprio 0
	s_setprio 1
	v_mfma_f32_16x16x32_bf16 v[136:139], v[148:151], v[164:167], v[136:139]
	v_mfma_f32_16x16x32_bf16 v[132:135], v[156:159], v[164:167], v[132:135]
	v_mfma_f32_16x16x32_bf16 v[104:107], v[148:151], v[178:181], v[104:107]
	v_mfma_f32_16x16x32_bf16 v[100:103], v[156:159], v[178:181], v[100:103]
	v_mfma_f32_16x16x32_bf16 v[86:89], v[148:151], v[186:189], v[86:89]
	v_mfma_f32_16x16x32_bf16 v[82:85], v[156:159], v[186:189], v[82:85]
	v_mfma_f32_16x16x32_bf16 v[70:73], v[148:151], v[200:203], v[70:73]
	v_mfma_f32_16x16x32_bf16 v[66:69], v[156:159], v[200:203], v[66:69]
	v_mfma_f32_16x16x32_bf16 v[136:139], v[152:155], v[168:171], v[136:139]
	v_mfma_f32_16x16x32_bf16 v[132:135], v[160:163], v[168:171], v[132:135]
	v_mfma_f32_16x16x32_bf16 v[104:107], v[152:155], v[182:185], v[104:107]
	v_mfma_f32_16x16x32_bf16 v[100:103], v[160:163], v[182:185], v[100:103]
	v_mfma_f32_16x16x32_bf16 v[86:89], v[152:155], v[190:193], v[86:89]
	v_mfma_f32_16x16x32_bf16 v[82:85], v[160:163], v[190:193], v[82:85]
	v_mfma_f32_16x16x32_bf16 v[70:73], v[152:155], v[208:211], v[70:73]
	v_mfma_f32_16x16x32_bf16 v[66:69], v[160:163], v[208:211], v[66:69]
	s_setprio 0
	s_barrier
	s_add_i32 s4, s6, s91
	v_lshl_add_u64 v[194:195], v[194:195], 0, s[42:43]
	s_mov_b32 m0, s4
	ds_read_b128 v[164:167], v207 offset:49152
	ds_read_b128 v[168:171], v207 offset:50176
	ds_read_b128 v[178:181], v207 offset:51200
	ds_read_b128 v[182:185], v207 offset:52224
	ds_read_b128 v[186:189], v207 offset:53248
	ds_read_b128 v[190:193], v207 offset:54272
	ds_read_b128 v[200:203], v207 offset:55296
	ds_read_b128 v[208:211], v207 offset:56320
	global_load_lds_dwordx4 v[194:195], off
	s_add_i32 m0, s4, 0x2000
	s_add_u32 s4, s78, 0x100080
	v_lshl_add_u64 v[194:195], v[212:213], 0, s[42:43]
	s_addc_u32 s5, s79, 0
	s_add_i32 s6, s7, s91
	global_load_lds_dwordx4 v[194:195], off
	v_lshl_add_u64 v[194:195], s[4:5], 0, v[172:173]
	s_mov_b32 m0, s6
	s_nop 0
	global_load_lds_dwordx4 v[194:195], off
	v_lshl_add_u64 v[194:195], s[4:5], 0, v[176:177]
	s_add_i32 m0, s6, 0x2000
	s_nop 0
	global_load_lds_dwordx4 v[194:195], off
	v_lshl_add_u64 v[194:195], v[214:215], 0, s[42:43]
	s_add_i32 m0, s44, 0x8000
	s_nop 0
	global_load_lds_dwordx4 v[194:195], off
	v_lshl_add_u64 v[194:195], v[216:217], 0, s[42:43]
	s_add_i32 m0, s44, 0xa000
	s_nop 0
	global_load_lds_dwordx4 v[194:195], off
	s_waitcnt vmcnt(8)
	s_waitcnt lgkmcnt(0)
	s_setprio 1
	s_barrier
	v_mfma_f32_16x16x32_bf16 v[62:65], v[112:115], v[164:167], v[62:65]
	v_mfma_f32_16x16x32_bf16 v[58:61], v[124:127], v[164:167], v[58:61]
	v_mfma_f32_16x16x32_bf16 v[46:49], v[112:115], v[178:181], v[46:49]
	v_mfma_f32_16x16x32_bf16 v[42:45], v[124:127], v[178:181], v[42:45]
	v_mfma_f32_16x16x32_bf16 v[30:33], v[112:115], v[186:189], v[30:33]
	v_mfma_f32_16x16x32_bf16 v[26:29], v[124:127], v[186:189], v[26:29]
	v_mfma_f32_16x16x32_bf16 v[14:17], v[112:115], v[200:203], v[14:17]
	v_mfma_f32_16x16x32_bf16 v[10:13], v[124:127], v[200:203], v[10:13]
	v_mfma_f32_16x16x32_bf16 v[62:65], v[116:119], v[168:171], v[62:65]
	v_mfma_f32_16x16x32_bf16 v[58:61], v[128:131], v[168:171], v[58:61]
	v_mfma_f32_16x16x32_bf16 v[46:49], v[116:119], v[182:185], v[46:49]
	v_mfma_f32_16x16x32_bf16 v[42:45], v[128:131], v[182:185], v[42:45]
	v_mfma_f32_16x16x32_bf16 v[30:33], v[116:119], v[190:193], v[30:33]
	v_mfma_f32_16x16x32_bf16 v[26:29], v[128:131], v[190:193], v[26:29]
	v_mfma_f32_16x16x32_bf16 v[14:17], v[116:119], v[208:211], v[14:17]
	v_mfma_f32_16x16x32_bf16 v[10:13], v[128:131], v[208:211], v[10:13]
	s_setprio 0
	s_setprio 1
	v_mfma_f32_16x16x32_bf16 v[54:57], v[148:151], v[164:167], v[54:57]
	v_mfma_f32_16x16x32_bf16 v[50:53], v[156:159], v[164:167], v[50:53]
	v_mfma_f32_16x16x32_bf16 v[38:41], v[148:151], v[178:181], v[38:41]
	v_mfma_f32_16x16x32_bf16 v[34:37], v[156:159], v[178:181], v[34:37]
	v_mfma_f32_16x16x32_bf16 v[22:25], v[148:151], v[186:189], v[22:25]
	v_mfma_f32_16x16x32_bf16 v[18:21], v[156:159], v[186:189], v[18:21]
	v_mfma_f32_16x16x32_bf16 v[6:9], v[148:151], v[200:203], v[6:9]
	v_mfma_f32_16x16x32_bf16 v[2:5], v[156:159], v[200:203], v[2:5]
	v_mfma_f32_16x16x32_bf16 v[54:57], v[152:155], v[168:171], v[54:57]
	v_mfma_f32_16x16x32_bf16 v[50:53], v[160:163], v[168:171], v[50:53]
	v_mfma_f32_16x16x32_bf16 v[38:41], v[152:155], v[182:185], v[38:41]
	v_mfma_f32_16x16x32_bf16 v[34:37], v[160:163], v[182:185], v[34:37]
	v_mfma_f32_16x16x32_bf16 v[22:25], v[152:155], v[190:193], v[22:25]
	v_mfma_f32_16x16x32_bf16 v[18:21], v[160:163], v[190:193], v[18:21]
	v_mfma_f32_16x16x32_bf16 v[6:9], v[152:155], v[208:211], v[6:9]
	v_mfma_f32_16x16x32_bf16 v[2:5], v[160:163], v[208:211], v[2:5]
	s_setprio 0
	s_barrier
	s_mov_b32 s100, 0
	s_add_i32 s95, s95, 2
	s_add_u32 s74, s74, 0x100
	s_addc_u32 s75, s75, 0
	s_add_u32 s71, s71, 0x100
	s_addc_u32 s94, s94, 0
	s_cmp_gt_u32 s95, 61
	s_cbranch_scc0 .LBB0_1116
	s_mov_b32 s100, 1
	s_and_b64 vcc, exec, s[10:11]
	s_cbranch_vccz .LBB0_1119
	s_barrier
	s_setprio 1

.LBB0_1138:
	s_setprio 0
	s_waitcnt vmcnt(0)
	v_readlane_b32 s8, v255, 31
	v_readlane_b32 s74, v255, 33
	v_readlane_b32 s9, v255, 32
	v_readlane_b32 s75, v255, 34
	s_barrier

.Lmy_sk12:
	s_waitcnt lgkmcnt(0)
	s_setprio 1
	s_barrier
	v_mfma_f32_16x16x32_bf16 v[62:65], v[90:93], v[164:167], v[62:65]
	v_mfma_f32_16x16x32_bf16 v[58:61], v[100:103], v[164:167], v[58:61]
	v_mfma_f32_16x16x32_bf16 v[46:49], v[90:93], v[172:175], v[46:49]
	v_mfma_f32_16x16x32_bf16 v[42:45], v[100:103], v[172:175], v[42:45]
	v_mfma_f32_16x16x32_bf16 v[30:33], v[90:93], v[180:183], v[30:33]
	v_mfma_f32_16x16x32_bf16 v[26:29], v[100:103], v[180:183], v[26:29]
	v_mfma_f32_16x16x32_bf16 v[14:17], v[90:93], v[188:191], v[14:17]
	v_mfma_f32_16x16x32_bf16 v[10:13], v[100:103], v[188:191], v[10:13]
	v_mfma_f32_16x16x32_bf16 v[62:65], v[94:97], v[168:171], v[62:65]
	v_mfma_f32_16x16x32_bf16 v[58:61], v[104:107], v[168:171], v[58:61]
	v_mfma_f32_16x16x32_bf16 v[46:49], v[94:97], v[176:179], v[46:49]
	v_mfma_f32_16x16x32_bf16 v[42:45], v[104:107], v[176:179], v[42:45]
	v_mfma_f32_16x16x32_bf16 v[30:33], v[94:97], v[184:187], v[30:33]
	v_mfma_f32_16x16x32_bf16 v[26:29], v[104:107], v[184:187], v[26:29]
	v_mfma_f32_16x16x32_bf16 v[14:17], v[94:97], v[192:195], v[14:17]
	v_mfma_f32_16x16x32_bf16 v[10:13], v[104:107], v[192:195], v[10:13]
	s_setprio 0
	s_setprio 1
	v_mfma_f32_16x16x32_bf16 v[54:57], v[108:111], v[164:167], v[54:57]
	v_mfma_f32_16x16x32_bf16 v[50:53], v[120:123], v[164:167], v[50:53]
	v_mfma_f32_16x16x32_bf16 v[38:41], v[108:111], v[172:175], v[38:41]
	v_mfma_f32_16x16x32_bf16 v[34:37], v[120:123], v[172:175], v[34:37]
	v_mfma_f32_16x16x32_bf16 v[22:25], v[108:111], v[180:183], v[22:25]
	v_mfma_f32_16x16x32_bf16 v[18:21], v[120:123], v[180:183], v[18:21]
	v_mfma_f32_16x16x32_bf16 v[6:9], v[108:111], v[188:191], v[6:9]
	v_mfma_f32_16x16x32_bf16 v[2:5], v[120:123], v[188:191], v[2:5]
	v_mfma_f32_16x16x32_bf16 v[54:57], v[112:115], v[168:171], v[54:57]
	v_mfma_f32_16x16x32_bf16 v[50:53], v[128:131], v[168:171], v[50:53]
	v_mfma_f32_16x16x32_bf16 v[38:41], v[112:115], v[176:179], v[38:41]
	v_mfma_f32_16x16x32_bf16 v[34:37], v[128:131], v[176:179], v[34:37]
	v_mfma_f32_16x16x32_bf16 v[22:25], v[112:115], v[184:187], v[22:25]
	v_mfma_f32_16x16x32_bf16 v[18:21], v[128:131], v[184:187], v[18:21]
	v_mfma_f32_16x16x32_bf16 v[6:9], v[112:115], v[192:195], v[6:9]
	v_mfma_f32_16x16x32_bf16 v[2:5], v[128:131], v[192:195], v[2:5]
	s_setprio 0
	s_barrier
	s_add_i32 s6, 0, 0x18000
	s_add_i32 s7, 0, 0x1c000
	v_add_u32_e32 v104, s6, v239
	v_add_u32_e32 v128, s7, v239
	ds_read_b128 v[90:93], v104
	ds_read_b128 v[94:97], v104 offset:1024
	ds_read_b128 v[100:103], v104 offset:2048
	ds_read_b128 v[104:107], v104 offset:3072
	ds_read_b128 v[108:111], v128
	ds_read_b128 v[112:115], v128 offset:1024
	ds_read_b128 v[120:123], v128 offset:2048
	ds_read_b128 v[128:131], v128 offset:3072
	s_add_u32 s4, s78, 0x100000
	s_addc_u32 s5, s79, 0
	v_lshl_add_u64 v[214:215], s[4:5], 0, v[98:99]
	s_add_i32 m0, s44, 0x4000
	ds_read_b128 v[164:167], v241 offset:32768
	ds_read_b128 v[168:171], v241 offset:33792
	ds_read_b128 v[172:175], v241 offset:34816
	ds_read_b128 v[176:179], v241 offset:35840
	ds_read_b128 v[180:183], v241 offset:36864
	ds_read_b128 v[184:187], v241 offset:37888
	ds_read_b128 v[188:191], v241 offset:38912
	ds_read_b128 v[192:195], v241 offset:39936
	global_load_lds_dwordx4 v[214:215], off
	v_lshl_add_u64 v[214:215], s[4:5], 0, v[206:207]
	s_add_i32 m0, s44, 0x6000
	s_nop 0
	global_load_lds_dwordx4 v[214:215], off
	s_waitcnt vmcnt(8)
	s_waitcnt lgkmcnt(0)
	s_setprio 1
	s_barrier
	v_mfma_f32_16x16x32_bf16 v[160:163], v[90:93], v[164:167], v[160:163]
	v_mfma_f32_16x16x32_bf16 v[156:159], v[100:103], v[164:167], v[156:159]
	v_mfma_f32_16x16x32_bf16 v[144:147], v[90:93], v[172:175], v[144:147]
	v_mfma_f32_16x16x32_bf16 v[140:143], v[100:103], v[172:175], v[140:143]
	v_mfma_f32_16x16x32_bf16 v[124:127], v[90:93], v[180:183], v[124:127]
	v_mfma_f32_16x16x32_bf16 v[116:119], v[100:103], v[180:183], v[116:119]
	v_mfma_f32_16x16x32_bf16 v[78:81], v[90:93], v[188:191], v[78:81]
	v_mfma_f32_16x16x32_bf16 v[74:77], v[100:103], v[188:191], v[74:77]
	v_mfma_f32_16x16x32_bf16 v[160:163], v[94:97], v[168:171], v[160:163]
	v_mfma_f32_16x16x32_bf16 v[156:159], v[104:107], v[168:171], v[156:159]
	v_mfma_f32_16x16x32_bf16 v[144:147], v[94:97], v[176:179], v[144:147]
	v_mfma_f32_16x16x32_bf16 v[140:143], v[104:107], v[176:179], v[140:143]
	v_mfma_f32_16x16x32_bf16 v[124:127], v[94:97], v[184:187], v[124:127]
	v_mfma_f32_16x16x32_bf16 v[116:119], v[104:107], v[184:187], v[116:119]
	v_mfma_f32_16x16x32_bf16 v[78:81], v[94:97], v[192:195], v[78:81]
	v_mfma_f32_16x16x32_bf16 v[74:77], v[104:107], v[192:195], v[74:77]
	s_setprio 0
	s_setprio 1
	v_mfma_f32_16x16x32_bf16 v[152:155], v[108:111], v[164:167], v[152:155]
	v_mfma_f32_16x16x32_bf16 v[148:151], v[120:123], v[164:167], v[148:151]
	v_mfma_f32_16x16x32_bf16 v[136:139], v[108:111], v[172:175], v[136:139]
	v_mfma_f32_16x16x32_bf16 v[132:135], v[120:123], v[172:175], v[132:135]
	v_mfma_f32_16x16x32_bf16 v[86:89], v[108:111], v[180:183], v[86:89]
	v_mfma_f32_16x16x32_bf16 v[82:85], v[120:123], v[180:183], v[82:85]
	v_mfma_f32_16x16x32_bf16 v[70:73], v[108:111], v[188:191], v[70:73]
	v_mfma_f32_16x16x32_bf16 v[66:69], v[120:123], v[188:191], v[66:69]
	v_mfma_f32_16x16x32_bf16 v[152:155], v[112:115], v[168:171], v[152:155]
	v_mfma_f32_16x16x32_bf16 v[148:151], v[128:131], v[168:171], v[148:151]
	v_mfma_f32_16x16x32_bf16 v[136:139], v[112:115], v[176:179], v[136:139]
	v_mfma_f32_16x16x32_bf16 v[132:135], v[128:131], v[176:179], v[132:135]
	v_mfma_f32_16x16x32_bf16 v[86:89], v[112:115], v[184:187], v[86:89]
	v_mfma_f32_16x16x32_bf16 v[82:85], v[128:131], v[184:187], v[82:85]
	v_mfma_f32_16x16x32_bf16 v[70:73], v[112:115], v[192:195], v[70:73]
	v_mfma_f32_16x16x32_bf16 v[66:69], v[128:131], v[192:195], v[66:69]
	s_setprio 0
	s_barrier
	s_add_i32 s4, s6, s91
	v_lshl_add_u64 v[200:201], v[200:201], 0, s[42:43]
	s_mov_b32 m0, s4
	ds_read_b128 v[164:167], v241 offset:49152
	ds_read_b128 v[168:171], v241 offset:50176
	ds_read_b128 v[172:175], v241 offset:51200
	ds_read_b128 v[176:179], v241 offset:52224
	ds_read_b128 v[180:183], v241 offset:53248
	ds_read_b128 v[184:187], v241 offset:54272
	ds_read_b128 v[188:191], v241 offset:55296
	ds_read_b128 v[192:195], v241 offset:56320
	global_load_lds_dwordx4 v[200:201], off
	s_add_i32 m0, s4, 0x2000
	s_add_u32 s4, s74, 0x100080
	v_lshl_add_u64 v[200:201], v[202:203], 0, s[42:43]
	s_addc_u32 s5, s75, 0
	s_add_i32 s6, s7, s91
	global_load_lds_dwordx4 v[200:201], off
	v_lshl_add_u64 v[200:201], s[4:5], 0, v[204:205]
	s_mov_b32 m0, s6
	s_nop 0
	global_load_lds_dwordx4 v[200:201], off
	v_lshl_add_u64 v[200:201], s[4:5], 0, v[208:209]
	s_add_i32 m0, s6, 0x2000
	s_nop 0
	global_load_lds_dwordx4 v[200:201], off
	v_lshl_add_u64 v[200:201], v[210:211], 0, s[42:43]
	s_add_i32 m0, s44, 0x8000
	s_nop 0
	global_load_lds_dwordx4 v[200:201], off
	v_lshl_add_u64 v[200:201], v[212:213], 0, s[42:43]
	s_add_i32 m0, s44, 0xa000
	s_nop 0
	global_load_lds_dwordx4 v[200:201], off
	s_waitcnt vmcnt(8)
	s_waitcnt lgkmcnt(0)
	s_setprio 1
	s_barrier
	v_mfma_f32_16x16x32_bf16 v[62:65], v[90:93], v[164:167], v[62:65]
	v_mfma_f32_16x16x32_bf16 v[58:61], v[100:103], v[164:167], v[58:61]
	v_mfma_f32_16x16x32_bf16 v[46:49], v[90:93], v[172:175], v[46:49]
	v_mfma_f32_16x16x32_bf16 v[42:45], v[100:103], v[172:175], v[42:45]
	v_mfma_f32_16x16x32_bf16 v[30:33], v[90:93], v[180:183], v[30:33]
	v_mfma_f32_16x16x32_bf16 v[26:29], v[100:103], v[180:183], v[26:29]
	v_mfma_f32_16x16x32_bf16 v[14:17], v[90:93], v[188:191], v[14:17]
	v_mfma_f32_16x16x32_bf16 v[10:13], v[100:103], v[188:191], v[10:13]
	v_mfma_f32_16x16x32_bf16 v[62:65], v[94:97], v[168:171], v[62:65]
	v_mfma_f32_16x16x32_bf16 v[58:61], v[104:107], v[168:171], v[58:61]
	v_mfma_f32_16x16x32_bf16 v[46:49], v[94:97], v[176:179], v[46:49]
	v_mfma_f32_16x16x32_bf16 v[42:45], v[104:107], v[176:179], v[42:45]
	v_mfma_f32_16x16x32_bf16 v[30:33], v[94:97], v[184:187], v[30:33]
	v_mfma_f32_16x16x32_bf16 v[26:29], v[104:107], v[184:187], v[26:29]
	v_mfma_f32_16x16x32_bf16 v[14:17], v[94:97], v[192:195], v[14:17]
	v_mfma_f32_16x16x32_bf16 v[10:13], v[104:107], v[192:195], v[10:13]
	s_setprio 0
	s_setprio 1
	v_mfma_f32_16x16x32_bf16 v[54:57], v[108:111], v[164:167], v[54:57]
	v_mfma_f32_16x16x32_bf16 v[50:53], v[120:123], v[164:167], v[50:53]
	v_mfma_f32_16x16x32_bf16 v[38:41], v[108:111], v[172:175], v[38:41]
	v_mfma_f32_16x16x32_bf16 v[34:37], v[120:123], v[172:175], v[34:37]
	v_mfma_f32_16x16x32_bf16 v[22:25], v[108:111], v[180:183], v[22:25]
	v_mfma_f32_16x16x32_bf16 v[18:21], v[120:123], v[180:183], v[18:21]
	v_mfma_f32_16x16x32_bf16 v[6:9], v[108:111], v[188:191], v[6:9]
	v_mfma_f32_16x16x32_bf16 v[2:5], v[120:123], v[188:191], v[2:5]
	v_mfma_f32_16x16x32_bf16 v[54:57], v[112:115], v[168:171], v[54:57]
	v_mfma_f32_16x16x32_bf16 v[50:53], v[128:131], v[168:171], v[50:53]
	v_mfma_f32_16x16x32_bf16 v[38:41], v[112:115], v[176:179], v[38:41]
	v_mfma_f32_16x16x32_bf16 v[34:37], v[128:131], v[176:179], v[34:37]
	v_mfma_f32_16x16x32_bf16 v[22:25], v[112:115], v[184:187], v[22:25]
	v_mfma_f32_16x16x32_bf16 v[18:21], v[128:131], v[184:187], v[18:21]
	v_mfma_f32_16x16x32_bf16 v[6:9], v[112:115], v[192:195], v[6:9]
	v_mfma_f32_16x16x32_bf16 v[2:5], v[128:131], v[192:195], v[2:5]
	s_setprio 0
	s_barrier
	s_mov_b32 s100, 0
	s_add_i32 s95, s95, 2
	s_add_u32 s70, s70, 0x100
	s_addc_u32 s71, s71, 0
	s_add_u32 s69, s69, 0x100
	s_addc_u32 s94, s94, 0
	s_cmp_gt_u32 s95, 61
	s_cbranch_scc0 .LBB0_1172
	s_mov_b32 s100, 1
	s_and_b64 vcc, exec, s[10:11]
	s_cbranch_vccz .LBB0_1175
	s_barrier
	s_setprio 1
